# v37 + redundant canonicalizing v_max before relu removed in the indexer scoring loop
# baseline (speedup 1.0000x reference)
; #define MFMA32(a, b, c) __builtin_amdgcn_mfma_f32_32x32x16_bf16((a), (b), (c), 0, 0, 0)
; DI unsigned fkey(float f) { unsigned u = __float_as_uint(f); return (u & 0x80000000u) ? ~u : (u | 0x80000000u); }
; DI void dsa_index_phase(unsigned char* lds, KParamPtr P, int wv) {
;     ...
;     for (int kt0 = wave * 4; kt0 < ntile; kt0 += 32) {
;       bf16x8 kf[4][4];
;       const unsigned ko = (unsigned)((b * SEQ + kt0 * 32 + l31) * EIN + C_IK + hh * 8);
; #pragma unroll
;       for (int u = 0; u < 4; ++u)
; #pragma unroll
;         for (int ks = 0; ks < 4; ++ks) kf[u][ks] = ldg8(proj + ko + (unsigned)(u * 32 * EIN + ks * 16));
; #pragma unroll
;       for (int u = 0; u < 4; ++u) {
;         f32x16 acc = zero16();
; #pragma unroll
;         for (int ks = 0; ks < 4; ++ks) acc = MFMA32(af[ks], kf[u][ks], acc);
;         float s0 = 0.f, s1 = 0.f;
; #pragma unroll
;         for (int i = 0; i < 8; ++i) { s0 += w[i] * fmaxf(acc[i], 0.f); s1 += w[8 + i] * fmaxf(acc[8 + i], 0.f); }
;         const int key = (kt0 + u) * 32 + l31;
;         s0 += 0.f; s1 += 0.f;
;         sc[(2 * hh) * 8192 + key] = s0;
;         sc[(2 * hh + 1) * 8192 + key] = s1;
;         if (key <= t0 + 2 * hh) atomicAdd(hist + (2 * hh) * 256 + (fkey(s0) >> 24), 1u);
;         if (key <= t0 + 2 * hh + 1) atomicAdd(hist + (2 * hh + 1) * 256 + (fkey(s1) >> 24), 1u);
.LBB0_855:
	v_lshl_add_u64 v[38:39], v[0:1], 1, s[84:85]
	global_load_dwordx4 v[2:5], v[38:39], off
	global_load_dwordx4 v[34:37], v[38:39], off offset:1024
	global_load_dwordx4 v[42:45], v[38:39], off offset:2048
	global_load_dwordx4 v[142:145], v[38:39], off offset:3072
	v_add_co_u32_e32 v6, vcc, 0x1000, v38
	s_mov_b32 s2, 0x2000
	s_nop 0
	v_addc_co_u32_e32 v7, vcc, 0, v39, vcc
	global_load_dwordx4 v[78:81], v[6:7], off
	global_load_dwordx4 v[74:77], v[6:7], off offset:1024
	global_load_dwordx4 v[70:73], v[6:7], off offset:2048
	global_load_dwordx4 v[66:69], v[6:7], off offset:3072
	v_add_co_u32_e32 v40, vcc, s2, v38
	s_mov_b32 s2, 0x3000
	s_nop 0
	v_addc_co_u32_e32 v41, vcc, 0, v39, vcc
	v_add_co_u32_e32 v46, vcc, s2, v38
	global_load_dwordx4 v[62:65], v[40:41], off
	global_load_dwordx4 v[54:57], v[40:41], off offset:1024
	v_addc_co_u32_e32 v47, vcc, 0, v39, vcc
	global_load_dwordx4 v[58:61], v[40:41], off offset:2048
	global_load_dwordx4 v[50:53], v[40:41], off offset:3072
	v_cmp_le_i32_e32 vcc, v121, v120
	s_waitcnt vmcnt(0) lgkmcnt(0)
	v_mfma_f32_32x32x16_bf16 v[2:17], v[18:21], v[2:5], 0
	v_mfma_f32_32x32x16_bf16 v[2:17], v[22:25], v[34:37], v[2:17]
	global_load_dwordx4 v[38:41], v[46:47], off
	global_load_dwordx4 v[34:37], v[46:47], off offset:1024
	v_mfma_f32_32x32x16_bf16 v[2:17], v[26:29], v[42:45], v[2:17]
	global_load_dwordx4 v[42:45], v[46:47], off offset:2048
	s_nop 0
	global_load_dwordx4 v[46:49], v[46:47], off offset:3072
	v_mfma_f32_32x32x16_bf16 v[2:17], v[30:33], v[142:145], v[2:17]
	s_nop 11
	v_max_f32_e32 v2, 0, v2
	v_max_f32_e32 v10, 0, v10
	v_max_f32_e32 v3, 0, v3
	v_max_f32_e32 v11, 0, v11
	v_fma_f32 v2, v124, v2, 0
	v_fma_f32 v10, v132, v10, 0
	v_max_f32_e32 v4, 0, v4
	v_max_f32_e32 v12, 0, v12
	v_fmac_f32_e32 v2, v125, v3
	v_fmac_f32_e32 v10, v133, v11
	v_max_f32_e32 v5, 0, v5
	v_max_f32_e32 v13, 0, v13
	v_fmac_f32_e32 v2, v126, v4
	v_fmac_f32_e32 v10, v134, v12
	v_max_f32_e32 v6, 0, v6
	v_max_f32_e32 v14, 0, v14
	v_fmac_f32_e32 v2, v127, v5
	v_fmac_f32_e32 v10, v135, v13
	v_max_f32_e32 v7, 0, v7
	v_max_f32_e32 v15, 0, v15
	v_fmac_f32_e32 v2, v128, v6
	v_fmac_f32_e32 v10, v136, v14
	v_max_f32_e32 v8, 0, v8
	v_max_f32_e32 v16, 0, v16
	v_fmac_f32_e32 v2, v129, v7
	v_fmac_f32_e32 v10, v137, v15
	v_max_f32_e32 v9, 0, v9
	v_max_f32_e32 v17, 0, v17
	v_fmac_f32_e32 v2, v130, v8
	v_fmac_f32_e32 v10, v138, v16
	v_fmac_f32_e32 v2, v131, v9
	v_fmac_f32_e32 v10, v139, v17
	v_add_f32_e32 v3, 0, v2
	v_add_f32_e32 v2, 0, v10
	ds_write2st64_b32 v122, v3, v2 offset1:128
	s_and_saveexec_b64 s[22:23], vcc
	s_cbranch_execz .LBB0_857
	v_not_b32_e32 v4, v3
	v_or_b32_e32 v5, 0x80000000, v3
	v_cmp_gt_i32_e32 vcc, 0, v3
	s_nop 1
	v_cndmask_b32_e32 v3, v5, v4, vcc
	v_lshrrev_b32_e32 v3, 24, v3
	v_lshl_add_u32 v3, v3, 2, v99
	ds_add_u32 v3, v214
